# pre-epilogue align barrier of the leading wave half moved after its first epilogue row group (P1, P8) so it works while the other half finishes its last MFMA segment
# baseline (speedup 1.0000x reference)
; #define PG8_STAGE(bufoff, gbase, voff) do { _Pragma("unroll") for (int _i = 0; _i < 2; ++_i) \
;         __builtin_amdgcn_global_load_lds((const unsigned*)((const char*)(gbase) + (voff)[_i]), (PG8_LAS unsigned*)(lds + (bufoff) + ldsw + _i * 8192), 16, 0, 0); } while (0)
; #define PG8_LDA(dst, b, h) do { _Pragma("unroll") for (int m = 0; m < 4; ++m) _Pragma("unroll") for (int k = 0; k < 2; ++k) dst[m][k] = *(const PG8_LAS bf16x8*)(lds + PG8_SA(b, h) + aoff + m * 2048 + k * 1024); } while (0)
; #define PG8_LDB(dst, b, h) do { _Pragma("unroll") for (int n = 0; n < 2; ++n) _Pragma("unroll") for (int k = 0; k < 2; ++k) dst[n][k] = *(const PG8_LAS bf16x8*)(lds + PG8_SB(b, h) + boff + n * 2048 + k * 1024); } while (0)
; #define PG8_MMA(ai, bj, At, Bt) do { __builtin_amdgcn_s_setprio(1); _Pragma("unroll") for (int m = 0; m < 4; ++m) _Pragma("unroll") for (int n = 0; n < 2; ++n) _Pragma("unroll") for (int k = 0; k < 2; ++k) \
;         acc[ai][bj][m][n] = __builtin_amdgcn_mfma_f32_16x16x32_bf16(Bt[n][k], At[m][k], acc[ai][bj][m][n], 0, 0, 0); __builtin_amdgcn_s_setprio(0); } while (0)
; #define PG8_WAIT_V(n) asm volatile("s_waitcnt vmcnt(" #n ")" ::: "memory")
; #define PG8_WAIT_L(n) asm volatile("s_waitcnt lgkmcnt(" #n ")" ::: "memory")
; #define PG8_BAR __builtin_amdgcn_s_barrier()
; #define PG8_SCHED __builtin_amdgcn_sched_barrier(0)
; template <class Epi, class Sched, bool ALIGN_EPI = false, bool SP2 = false>
; __device__ __forceinline__ void gemm_phase(PG8_LAS unsigned char* lds, const Gemm g, const Sched& S, const Epi& E) {
;     ...
;             PG8_LDB(B0, 0, 0); PG8_LDB(B1, 0, 1); PG8_SCHED; PG8_LDA(At, 0, 0); PG8_STAGE(PG8_SA(1, 1), a1 + hstep, voffA);
;             PG8_WAIT_V(8); PG8_WAIT_L(0); PG8_BAR; PG8_MMA(0, 0, At, B0); PG8_MMA(0, 1, At, B1); PG8_BAR; PG8_SCHED;
;             PG8_LDA(At, 0, 1); PG8_STAGE(PG8_SB(0, 0), b2, voffB); PG8_STAGE(PG8_SB(0, 1), b2 + hstep, voffB); PG8_STAGE(PG8_SA(0, 0), a2, voffA);
;             PG8_WAIT_V(8); PG8_WAIT_L(0); PG8_BAR; PG8_MMA(1, 0, At, B0); PG8_MMA(1, 1, At, B1); PG8_BAR; PG8_SCHED;
.LBB0_134:
	ds_read_b128 v[136:139], v151
	ds_read_b128 v[168:171], v151 offset:1024
	ds_read_b128 v[176:179], v151 offset:2048
	ds_read_b128 v[180:183], v151 offset:3072
	ds_read_b128 v[184:187], v164
	ds_read_b128 v[188:191], v164 offset:1024
	ds_read_b128 v[192:195], v164 offset:2048
	ds_read_b128 v[196:199], v164 offset:3072
	s_add_u32 s36, s34, 0xfffc0080
	s_addc_u32 s37, s35, -1
	s_cmp_eq_u32 s89, 12
	s_cselect_b32 s39, s1, s37
	s_cselect_b32 s38, s7, s36
	s_cselect_b32 s37, s15, s88
	s_cselect_b32 s36, s27, s87
	v_lshl_add_u64 v[228:229], s[34:35], 0, v[128:129]
	s_add_i32 m0, s33, 0xc000
	ds_read_b128 v[200:203], v165
	ds_read_b128 v[204:207], v165 offset:1024
	ds_read_b128 v[208:211], v165 offset:2048
	ds_read_b128 v[212:215], v165 offset:3072
	ds_read_b128 v[216:219], v165 offset:4096
	ds_read_b128 v[220:223], v165 offset:5120
	ds_read_b128 v[224:227], v165 offset:6144
	ds_read_b128 v[240:243], v165 offset:7168
	global_load_lds_dwordx4 v[228:229], off
	v_lshl_add_u64 v[228:229], s[34:35], 0, v[130:131]
	s_add_i32 m0, s33, 0xe000
	s_nop 0
	global_load_lds_dwordx4 v[228:229], off
	s_waitcnt vmcnt(8)
	s_waitcnt lgkmcnt(0)
	s_setprio 1
	s_barrier
	v_mfma_f32_16x16x32_bf16 v[124:127], v[136:139], v[200:203], v[124:127]
	v_mfma_f32_16x16x32_bf16 v[116:119], v[176:179], v[200:203], v[116:119]
	v_mfma_f32_16x16x32_bf16 v[108:111], v[136:139], v[208:211], v[108:111]
	v_mfma_f32_16x16x32_bf16 v[100:103], v[176:179], v[208:211], v[100:103]
	v_mfma_f32_16x16x32_bf16 v[92:95], v[136:139], v[216:219], v[92:95]
	v_mfma_f32_16x16x32_bf16 v[84:87], v[176:179], v[216:219], v[84:87]
	v_mfma_f32_16x16x32_bf16 v[76:79], v[136:139], v[224:227], v[76:79]
	v_mfma_f32_16x16x32_bf16 v[68:71], v[176:179], v[224:227], v[68:71]
	v_mfma_f32_16x16x32_bf16 v[124:127], v[168:171], v[204:207], v[124:127]
	v_mfma_f32_16x16x32_bf16 v[116:119], v[180:183], v[204:207], v[116:119]
	v_mfma_f32_16x16x32_bf16 v[108:111], v[168:171], v[212:215], v[108:111]
	v_mfma_f32_16x16x32_bf16 v[100:103], v[180:183], v[212:215], v[100:103]
	v_mfma_f32_16x16x32_bf16 v[92:95], v[168:171], v[220:223], v[92:95]
	v_mfma_f32_16x16x32_bf16 v[84:87], v[180:183], v[220:223], v[84:87]
	v_mfma_f32_16x16x32_bf16 v[76:79], v[168:171], v[240:243], v[76:79]
	v_mfma_f32_16x16x32_bf16 v[68:71], v[180:183], v[240:243], v[68:71]
	s_setprio 0
	s_setprio 1
	v_mfma_f32_16x16x32_bf16 v[120:123], v[184:187], v[200:203], v[120:123]
	v_mfma_f32_16x16x32_bf16 v[112:115], v[192:195], v[200:203], v[112:115]
	v_mfma_f32_16x16x32_bf16 v[104:107], v[184:187], v[208:211], v[104:107]
	v_mfma_f32_16x16x32_bf16 v[96:99], v[192:195], v[208:211], v[96:99]
	v_mfma_f32_16x16x32_bf16 v[88:91], v[184:187], v[216:219], v[88:91]
	v_mfma_f32_16x16x32_bf16 v[80:83], v[192:195], v[216:219], v[80:83]
	v_mfma_f32_16x16x32_bf16 v[72:75], v[184:187], v[224:227], v[72:75]
	v_mfma_f32_16x16x32_bf16 v[64:67], v[192:195], v[224:227], v[64:67]
	v_mfma_f32_16x16x32_bf16 v[120:123], v[188:191], v[204:207], v[120:123]
	v_mfma_f32_16x16x32_bf16 v[112:115], v[196:199], v[204:207], v[112:115]
	v_mfma_f32_16x16x32_bf16 v[104:107], v[188:191], v[212:215], v[104:107]
	v_mfma_f32_16x16x32_bf16 v[96:99], v[196:199], v[212:215], v[96:99]
	v_mfma_f32_16x16x32_bf16 v[88:91], v[188:191], v[220:223], v[88:91]
	v_mfma_f32_16x16x32_bf16 v[80:83], v[196:199], v[220:223], v[80:83]
	v_mfma_f32_16x16x32_bf16 v[72:75], v[188:191], v[240:243], v[72:75]
	v_mfma_f32_16x16x32_bf16 v[64:67], v[196:199], v[240:243], v[64:67]
	s_barrier
	s_setprio 0
	s_add_i32 s90, s82, s3
	v_lshl_add_u64 v[228:229], s[36:37], 0, v[158:159]
	s_mov_b32 m0, s90
	ds_read_b128 v[200:203], v165 offset:16384
	ds_read_b128 v[204:207], v165 offset:17408
	ds_read_b128 v[208:211], v165 offset:18432
	ds_read_b128 v[212:215], v165 offset:19456
	ds_read_b128 v[216:219], v165 offset:20480
	ds_read_b128 v[220:223], v165 offset:21504
	ds_read_b128 v[224:227], v165 offset:22528
	ds_read_b128 v[240:243], v165 offset:23552
	global_load_lds_dwordx4 v[228:229], off
	s_add_i32 m0, s90, 0x2000
	s_add_u32 s90, s36, 0x40000
	v_lshl_add_u64 v[244:245], s[36:37], 0, v[162:163]
	s_addc_u32 s91, s37, 0
	s_add_i32 s93, s83, s3
	global_load_lds_dwordx4 v[244:245], off
	v_lshl_add_u64 v[248:249], s[90:91], 0, v[158:159]
	s_mov_b32 m0, s93
	v_lshl_add_u64 v[250:251], s[38:39], 0, v[160:161]
	global_load_lds_dwordx4 v[248:249], off
	v_lshl_add_u64 v[248:249], s[90:91], 0, v[162:163]
	s_add_i32 m0, s93, 0x2000
	s_nop 0
	global_load_lds_dwordx4 v[248:249], off
	v_lshl_add_u64 v[248:249], s[38:39], 0, v[156:157]
	s_mov_b32 m0, s33
	s_nop 0
	global_load_lds_dwordx4 v[248:249], off
	s_mov_b32 m0, s40
	s_nop 0
	global_load_lds_dwordx4 v[250:251], off
	s_waitcnt vmcnt(8)
	s_waitcnt lgkmcnt(0)
	s_setprio 1
	s_barrier
; #define PG8_STAGE(bufoff, gbase, voff) do { _Pragma("unroll") for (int _i = 0; _i < 2; ++_i) \
;         __builtin_amdgcn_global_load_lds((const unsigned*)((const char*)(gbase) + (voff)[_i]), (PG8_LAS unsigned*)(lds + (bufoff) + ldsw + _i * 8192), 16, 0, 0); } while (0)
; #define PG8_LDA(dst, b, h) do { _Pragma("unroll") for (int m = 0; m < 4; ++m) _Pragma("unroll") for (int k = 0; k < 2; ++k) dst[m][k] = *(const PG8_LAS bf16x8*)(lds + PG8_SA(b, h) + aoff + m * 2048 + k * 1024); } while (0)
; #define PG8_LDB(dst, b, h) do { _Pragma("unroll") for (int n = 0; n < 2; ++n) _Pragma("unroll") for (int k = 0; k < 2; ++k) dst[n][k] = *(const PG8_LAS bf16x8*)(lds + PG8_SB(b, h) + boff + n * 2048 + k * 1024); } while (0)
; #define PG8_MMA(ai, bj, At, Bt) do { __builtin_amdgcn_s_setprio(1); _Pragma("unroll") for (int m = 0; m < 4; ++m) _Pragma("unroll") for (int n = 0; n < 2; ++n) _Pragma("unroll") for (int k = 0; k < 2; ++k) \
;         acc[ai][bj][m][n] = __builtin_amdgcn_mfma_f32_16x16x32_bf16(Bt[n][k], At[m][k], acc[ai][bj][m][n], 0, 0, 0); __builtin_amdgcn_s_setprio(0); } while (0)
; #define PG8_WAIT_V(n) asm volatile("s_waitcnt vmcnt(" #n ")" ::: "memory")
; #define PG8_WAIT_L(n) asm volatile("s_waitcnt lgkmcnt(" #n ")" ::: "memory")
; #define PG8_BAR __builtin_amdgcn_s_barrier()
; #define PG8_SCHED __builtin_amdgcn_sched_barrier(0)
; template <class Epi, class Sched, bool ALIGN_EPI = false, bool SP2 = false>
; __device__ __forceinline__ void gemm_phase(PG8_LAS unsigned char* lds, const Gemm g, const Sched& S, const Epi& E) {
;     ...
;             PG8_WAIT_V(8); PG8_WAIT_L(0); PG8_BAR; PG8_MMA(1, 0, At, B0); PG8_MMA(1, 1, At, B1); PG8_BAR; PG8_SCHED;
;             PG8_LDB(B0, 1, 0); PG8_LDB(B1, 1, 1); PG8_SCHED; PG8_LDA(At, 1, 0); PG8_STAGE(PG8_SA(0, 1), a2 + hstep, voffA);
;             PG8_WAIT_V(8); PG8_WAIT_L(0); PG8_BAR; PG8_MMA(0, 0, At, B0); PG8_MMA(0, 1, At, B1); PG8_BAR; PG8_SCHED;
	v_mfma_f32_16x16x32_bf16 v[60:63], v[136:139], v[200:203], v[60:63]
	v_mfma_f32_16x16x32_bf16 v[52:55], v[176:179], v[200:203], v[52:55]
	v_mfma_f32_16x16x32_bf16 v[44:47], v[136:139], v[208:211], v[44:47]
	v_mfma_f32_16x16x32_bf16 v[36:39], v[176:179], v[208:211], v[36:39]
	v_mfma_f32_16x16x32_bf16 v[28:31], v[136:139], v[216:219], v[28:31]
	v_mfma_f32_16x16x32_bf16 v[20:23], v[176:179], v[216:219], v[20:23]
	v_mfma_f32_16x16x32_bf16 v[12:15], v[136:139], v[224:227], v[12:15]
	v_mfma_f32_16x16x32_bf16 v[4:7], v[176:179], v[224:227], v[4:7]
	v_mfma_f32_16x16x32_bf16 v[60:63], v[168:171], v[204:207], v[60:63]
	v_mfma_f32_16x16x32_bf16 v[52:55], v[180:183], v[204:207], v[52:55]
	v_mfma_f32_16x16x32_bf16 v[44:47], v[168:171], v[212:215], v[44:47]
	v_mfma_f32_16x16x32_bf16 v[36:39], v[180:183], v[212:215], v[36:39]
	v_mfma_f32_16x16x32_bf16 v[28:31], v[168:171], v[220:223], v[28:31]
	v_mfma_f32_16x16x32_bf16 v[20:23], v[180:183], v[220:223], v[20:23]
	v_mfma_f32_16x16x32_bf16 v[12:15], v[168:171], v[240:243], v[12:15]
	v_mfma_f32_16x16x32_bf16 v[4:7], v[180:183], v[240:243], v[4:7]
	s_setprio 0
	s_setprio 1
	v_mfma_f32_16x16x32_bf16 v[56:59], v[184:187], v[200:203], v[56:59]
	v_mfma_f32_16x16x32_bf16 v[48:51], v[192:195], v[200:203], v[48:51]
	v_mfma_f32_16x16x32_bf16 v[40:43], v[184:187], v[208:211], v[40:43]
	v_mfma_f32_16x16x32_bf16 v[32:35], v[192:195], v[208:211], v[32:35]
	v_mfma_f32_16x16x32_bf16 v[24:27], v[184:187], v[216:219], v[24:27]
	v_mfma_f32_16x16x32_bf16 v[16:19], v[192:195], v[216:219], v[16:19]
	v_mfma_f32_16x16x32_bf16 v[8:11], v[184:187], v[224:227], v[8:11]
	v_mfma_f32_16x16x32_bf16 v[0:3], v[192:195], v[224:227], v[0:3]
	v_mfma_f32_16x16x32_bf16 v[56:59], v[188:191], v[204:207], v[56:59]
	v_mfma_f32_16x16x32_bf16 v[48:51], v[196:199], v[204:207], v[48:51]
	v_mfma_f32_16x16x32_bf16 v[40:43], v[188:191], v[212:215], v[40:43]
	v_mfma_f32_16x16x32_bf16 v[32:35], v[196:199], v[212:215], v[32:35]
	v_mfma_f32_16x16x32_bf16 v[24:27], v[188:191], v[220:223], v[24:27]
	v_mfma_f32_16x16x32_bf16 v[16:19], v[196:199], v[220:223], v[16:19]
	v_mfma_f32_16x16x32_bf16 v[8:11], v[188:191], v[240:243], v[8:11]
	v_mfma_f32_16x16x32_bf16 v[0:3], v[196:199], v[240:243], v[0:3]
	s_barrier
	s_setprio 0
	s_add_i32 s90, 0, 0x18000
	v_add_u32_e32 v172, s90, v148
	s_add_i32 s91, 0, 0x1c000
	ds_read_b128 v[136:139], v172
	ds_read_b128 v[168:171], v172 offset:1024
	ds_read_b128 v[176:179], v172 offset:2048
	ds_read_b128 v[180:183], v172 offset:3072
	v_add_u32_e32 v172, s91, v148
	ds_read_b128 v[184:187], v172
	ds_read_b128 v[188:191], v172 offset:1024
	ds_read_b128 v[192:195], v172 offset:2048
	ds_read_b128 v[196:199], v172 offset:3072
	s_add_u32 s38, s38, 0x40000
	s_addc_u32 s39, s39, 0
	s_mov_b32 m0, s41
	v_lshl_add_u64 v[252:253], s[38:39], 0, v[156:157]
	ds_read_b128 v[200:203], v165 offset:32768
	ds_read_b128 v[204:207], v165 offset:33792
	ds_read_b128 v[208:211], v165 offset:34816
	ds_read_b128 v[212:215], v165 offset:35840
	ds_read_b128 v[216:219], v165 offset:36864
	ds_read_b128 v[220:223], v165 offset:37888
	ds_read_b128 v[224:227], v165 offset:38912
	ds_read_b128 v[240:243], v165 offset:39936
	global_load_lds_dwordx4 v[252:253], off
	v_lshl_add_u64 v[252:253], s[38:39], 0, v[160:161]
	s_mov_b32 m0, s42
	s_nop 0
	global_load_lds_dwordx4 v[252:253], off
	s_waitcnt vmcnt(8)
	s_waitcnt lgkmcnt(0)
	s_setprio 1
	s_barrier
	v_mfma_f32_16x16x32_bf16 v[124:127], v[136:139], v[200:203], v[124:127]
	v_mfma_f32_16x16x32_bf16 v[116:119], v[176:179], v[200:203], v[116:119]
	v_mfma_f32_16x16x32_bf16 v[108:111], v[136:139], v[208:211], v[108:111]
	v_mfma_f32_16x16x32_bf16 v[100:103], v[176:179], v[208:211], v[100:103]
	v_mfma_f32_16x16x32_bf16 v[92:95], v[136:139], v[216:219], v[92:95]
	v_mfma_f32_16x16x32_bf16 v[84:87], v[176:179], v[216:219], v[84:87]
	v_mfma_f32_16x16x32_bf16 v[76:79], v[136:139], v[224:227], v[76:79]
	v_mfma_f32_16x16x32_bf16 v[68:71], v[176:179], v[224:227], v[68:71]
	v_mfma_f32_16x16x32_bf16 v[124:127], v[168:171], v[204:207], v[124:127]
	v_mfma_f32_16x16x32_bf16 v[116:119], v[180:183], v[204:207], v[116:119]
	v_mfma_f32_16x16x32_bf16 v[108:111], v[168:171], v[212:215], v[108:111]
	v_mfma_f32_16x16x32_bf16 v[100:103], v[180:183], v[212:215], v[100:103]
	v_mfma_f32_16x16x32_bf16 v[92:95], v[168:171], v[220:223], v[92:95]
	v_mfma_f32_16x16x32_bf16 v[84:87], v[180:183], v[220:223], v[84:87]
	v_mfma_f32_16x16x32_bf16 v[76:79], v[168:171], v[240:243], v[76:79]
	v_mfma_f32_16x16x32_bf16 v[68:71], v[180:183], v[240:243], v[68:71]
	s_setprio 0
	s_setprio 1
	v_mfma_f32_16x16x32_bf16 v[120:123], v[184:187], v[200:203], v[120:123]
	v_mfma_f32_16x16x32_bf16 v[112:115], v[192:195], v[200:203], v[112:115]
	v_mfma_f32_16x16x32_bf16 v[104:107], v[184:187], v[208:211], v[104:107]
	v_mfma_f32_16x16x32_bf16 v[96:99], v[192:195], v[208:211], v[96:99]
	v_mfma_f32_16x16x32_bf16 v[88:91], v[184:187], v[216:219], v[88:91]
	v_mfma_f32_16x16x32_bf16 v[80:83], v[192:195], v[216:219], v[80:83]
	v_mfma_f32_16x16x32_bf16 v[72:75], v[184:187], v[224:227], v[72:75]
	v_mfma_f32_16x16x32_bf16 v[64:67], v[192:195], v[224:227], v[64:67]
	v_mfma_f32_16x16x32_bf16 v[120:123], v[188:191], v[204:207], v[120:123]
	v_mfma_f32_16x16x32_bf16 v[112:115], v[196:199], v[204:207], v[112:115]
	v_mfma_f32_16x16x32_bf16 v[104:107], v[188:191], v[212:215], v[104:107]
	v_mfma_f32_16x16x32_bf16 v[96:99], v[196:199], v[212:215], v[96:99]
	v_mfma_f32_16x16x32_bf16 v[88:91], v[188:191], v[220:223], v[88:91]
	v_mfma_f32_16x16x32_bf16 v[80:83], v[196:199], v[220:223], v[80:83]
	v_mfma_f32_16x16x32_bf16 v[72:75], v[188:191], v[240:243], v[72:75]
	v_mfma_f32_16x16x32_bf16 v[64:67], v[196:199], v[240:243], v[64:67]
	s_barrier
; __device__ __forceinline__ float row_rstd(const float* ss, int row) {
;     const f32x4* p = (const f32x4*)(ss + (size_t)row * 16);
;     const f32x4 a = p[0], b = p[1], c = p[2], d = p[3];
;     const float s = (((a[0] + a[1]) + (a[2] + a[3])) + ((b[0] + b[1]) + (b[2] + b[3]))) + (((c[0] + c[1]) + (c[2] + c[3])) + ((d[0] + d[1]) + (d[2] + d[3])));
; template <class Epi, class Sched, bool ALIGN_EPI = false, bool SP2 = false>
; __device__ __forceinline__ void gemm_phase(PG8_LAS unsigned char* lds, const Gemm g, const Sched& S, const Epi& E) {
;     ...
;             PG8_WAIT_V(8); PG8_WAIT_L(0); PG8_BAR; PG8_MMA(0, 0, At, B0); PG8_MMA(0, 1, At, B1); PG8_BAR; PG8_SCHED;
;             PG8_LDA(At, 1, 1); PG8_STAGE(PG8_SB(1, 0), b3, voffB); PG8_STAGE(PG8_SB(1, 1), b3 + hstep, voffB); PG8_STAGE(PG8_SA(1, 0), a3, voffA);
;             PG8_WAIT_V(8); PG8_WAIT_L(0); PG8_BAR; PG8_MMA(1, 0, At, B0); PG8_MMA(1, 1, At, B1); PG8_BAR; PG8_SCHED;
;             } else {
;             PG8_LDB(B0, 0, 0); PG8_SCHED; PG8_LDA(At, 0, 0); PG8_STAGE(PG8_SA(1, 1), a1 + hstep, voffA);
;             PG8_WAIT_L(8); PG8_BAR; PG8_WAIT_L(0); PG8_MMA(0, 0, At, B0); PG8_BAR; PG8_SCHED;
;             PG8_LDB(B1, 0, 1); PG8_STAGE(PG8_SB(0, 0), b2, voffB);
;             PG8_BAR; PG8_WAIT_L(0); PG8_MMA(0, 1, At, B1); PG8_BAR;
;             PG8_LDA(At, 0, 1); PG8_STAGE(PG8_SA(0, 0), a2, voffA);
;             PG8_BAR; PG8_WAIT_L(0); PG8_MMA(1, 0, At, B0); PG8_BAR; PG8_SCHED;
;             PG8_STAGE(PG8_SB(0, 1), b2 + hstep, voffB);
;             PG8_WAIT_V(6); PG8_BAR; PG8_MMA(1, 1, At, B1); PG8_BAR;
;             PG8_LDB(B0, 1, 0); PG8_SCHED; PG8_LDA(At, 1, 0); PG8_STAGE(PG8_SA(0, 1), a2 + hstep, voffA);
;             PG8_WAIT_L(8); PG8_BAR; PG8_WAIT_L(0); PG8_MMA(0, 0, At, B0); PG8_BAR; PG8_SCHED;
;             PG8_LDB(B1, 1, 1); PG8_STAGE(PG8_SB(1, 0), b3, voffB);
;             PG8_BAR; PG8_WAIT_L(0); PG8_MMA(0, 1, At, B1); PG8_BAR;
;             PG8_LDA(At, 1, 1); PG8_STAGE(PG8_SA(1, 0), a3, voffA);
;             PG8_BAR; PG8_WAIT_L(0); PG8_MMA(1, 0, At, B0); PG8_BAR; PG8_SCHED;
;             PG8_STAGE(PG8_SB(1, 1), b3 + hstep, voffB);
;             PG8_WAIT_V(6); PG8_BAR; PG8_MMA(1, 1, At, B1); PG8_BAR;
;             }
;         }
;         if constexpr (ALIGN_EPI) { if (wr == 0) PG8_BAR; }
;         if constexpr (!Epi::AFTER_DRAIN) { E(acc, cur, wr, wc, fr, fq); S.done(cur); }
	s_setprio 0
	s_add_i32 s38, s90, s3
	v_lshl_add_u64 v[228:229], v[228:229], 0, s[10:11]
	s_mov_b32 m0, s38
	ds_read_b128 v[200:203], v165 offset:49152
	ds_read_b128 v[204:207], v165 offset:50176
	ds_read_b128 v[208:211], v165 offset:51200
	ds_read_b128 v[212:215], v165 offset:52224
	ds_read_b128 v[216:219], v165 offset:53248
	ds_read_b128 v[220:223], v165 offset:54272
	ds_read_b128 v[224:227], v165 offset:55296
	ds_read_b128 v[240:243], v165 offset:56320
	global_load_lds_dwordx4 v[228:229], off
	s_add_i32 m0, s38, 0x2000
	s_add_u32 s36, s36, 0x40080
	v_lshl_add_u64 v[228:229], v[244:245], 0, s[10:11]
	s_addc_u32 s37, s37, 0
	s_add_i32 s38, s91, s3
	global_load_lds_dwordx4 v[228:229], off
	v_lshl_add_u64 v[228:229], s[36:37], 0, v[158:159]
	s_mov_b32 m0, s38
	s_nop 0
	global_load_lds_dwordx4 v[228:229], off
	v_lshl_add_u64 v[228:229], s[36:37], 0, v[162:163]
	s_add_i32 m0, s38, 0x2000
	s_nop 0
	global_load_lds_dwordx4 v[228:229], off
	v_lshl_add_u64 v[228:229], v[248:249], 0, s[10:11]
	s_mov_b32 m0, s44
	s_nop 0
	global_load_lds_dwordx4 v[228:229], off
	v_lshl_add_u64 v[228:229], v[250:251], 0, s[10:11]
	s_mov_b32 m0, s45
	s_nop 0
	global_load_lds_dwordx4 v[228:229], off
	s_waitcnt vmcnt(8)
	s_waitcnt lgkmcnt(0)
	s_setprio 1
	s_barrier
	v_mfma_f32_16x16x32_bf16 v[60:63], v[136:139], v[200:203], v[60:63]
	v_mfma_f32_16x16x32_bf16 v[52:55], v[176:179], v[200:203], v[52:55]
	v_mfma_f32_16x16x32_bf16 v[44:47], v[136:139], v[208:211], v[44:47]
	v_mfma_f32_16x16x32_bf16 v[36:39], v[176:179], v[208:211], v[36:39]
	v_mfma_f32_16x16x32_bf16 v[28:31], v[136:139], v[216:219], v[28:31]
	v_mfma_f32_16x16x32_bf16 v[20:23], v[176:179], v[216:219], v[20:23]
	v_mfma_f32_16x16x32_bf16 v[12:15], v[136:139], v[224:227], v[12:15]
	v_mfma_f32_16x16x32_bf16 v[4:7], v[176:179], v[224:227], v[4:7]
	v_mfma_f32_16x16x32_bf16 v[60:63], v[168:171], v[204:207], v[60:63]
	v_mfma_f32_16x16x32_bf16 v[52:55], v[180:183], v[204:207], v[52:55]
	v_mfma_f32_16x16x32_bf16 v[44:47], v[168:171], v[212:215], v[44:47]
	v_mfma_f32_16x16x32_bf16 v[36:39], v[180:183], v[212:215], v[36:39]
	v_mfma_f32_16x16x32_bf16 v[28:31], v[168:171], v[220:223], v[28:31]
	v_mfma_f32_16x16x32_bf16 v[20:23], v[180:183], v[220:223], v[20:23]
	v_mfma_f32_16x16x32_bf16 v[12:15], v[168:171], v[240:243], v[12:15]
	v_mfma_f32_16x16x32_bf16 v[4:7], v[180:183], v[240:243], v[4:7]
	s_setprio 0
	s_setprio 1
	v_mfma_f32_16x16x32_bf16 v[56:59], v[184:187], v[200:203], v[56:59]
	v_mfma_f32_16x16x32_bf16 v[48:51], v[192:195], v[200:203], v[48:51]
	v_mfma_f32_16x16x32_bf16 v[40:43], v[184:187], v[208:211], v[40:43]
	v_mfma_f32_16x16x32_bf16 v[32:35], v[192:195], v[208:211], v[32:35]
	v_mfma_f32_16x16x32_bf16 v[24:27], v[184:187], v[216:219], v[24:27]
	v_mfma_f32_16x16x32_bf16 v[16:19], v[192:195], v[216:219], v[16:19]
	v_mfma_f32_16x16x32_bf16 v[8:11], v[184:187], v[224:227], v[8:11]
	v_mfma_f32_16x16x32_bf16 v[0:3], v[192:195], v[224:227], v[0:3]
	v_mfma_f32_16x16x32_bf16 v[56:59], v[188:191], v[204:207], v[56:59]
	v_mfma_f32_16x16x32_bf16 v[48:51], v[196:199], v[204:207], v[48:51]
	v_mfma_f32_16x16x32_bf16 v[40:43], v[188:191], v[212:215], v[40:43]
	v_mfma_f32_16x16x32_bf16 v[32:35], v[196:199], v[212:215], v[32:35]
	v_mfma_f32_16x16x32_bf16 v[24:27], v[188:191], v[220:223], v[24:27]
	v_mfma_f32_16x16x32_bf16 v[16:19], v[196:199], v[220:223], v[16:19]
	v_mfma_f32_16x16x32_bf16 v[8:11], v[188:191], v[240:243], v[8:11]
	v_mfma_f32_16x16x32_bf16 v[0:3], v[196:199], v[240:243], v[0:3]
	s_barrier
	s_setprio 0
	s_add_i32 s89, s89, 2
	s_add_u32 s34, s34, 0x100
	s_addc_u32 s35, s35, 0
	s_add_u32 s87, s87, 0x100
	s_addc_u32 s88, s88, 0
	s_cmp_gt_u32 s89, 13
	s_cbranch_scc0 .LBB0_134
.LBB0_137:
	s_lshl_b32 s15, s0, 8
	s_cmp_lg_u32 s0, s2
	s_cselect_b64 s[34:35], -1, 0
	v_add_u32_e32 v138, s15, v147
	s_mov_b64 s[0:1], -1
	s_and_b64 vcc, exec, s[34:35]
	v_ashrrev_i32_e32 v139, 31, v138
	s_cbranch_vccz .LBB0_139
	v_lshlrev_b64 v[136:137], 6, v[138:139]
	v_lshl_add_u64 v[136:137], s[72:73], 0, v[136:137]
	global_load_dwordx4 v[168:171], v[136:137], off
	global_load_dwordx4 v[176:179], v[136:137], off offset:32
	global_load_dwordx4 v[180:183], v[136:137], off offset:16
	global_load_dwordx4 v[184:187], v[136:137], off offset:48
	s_waitcnt vmcnt(0)
	v_mov_b32_e32 v136, v168
	v_mov_b32_e32 v137, v176
	v_mov_b32_e32 v176, v169
	v_mov_b32_e32 v168, v170
	v_mov_b32_e32 v169, v178
	v_mov_b32_e32 v178, v171
	v_mov_b32_e32 v170, v180
	v_mov_b32_e32 v171, v184
	v_mov_b32_e32 v184, v181
	v_mov_b32_e32 v180, v182
	v_mov_b32_e32 v181, v186
	v_mov_b32_e32 v186, v183
	v_pk_add_f32 v[136:137], v[136:137], v[176:177]
	v_pk_add_f32 v[168:169], v[168:169], v[178:179]
	v_pk_add_f32 v[170:171], v[170:171], v[184:185]
	v_pk_add_f32 v[176:177], v[180:181], v[186:187]
	v_pk_add_f32 v[136:137], v[136:137], v[168:169]
	v_pk_add_f32 v[168:169], v[170:171], v[176:177]
	s_nop 0
	v_pk_add_f32 v[136:137], v[136:137], v[168:169]
	s_nop 0
	v_add_f32_e32 v136, v136, v137
	v_fmamk_f32 v136, v136, 0x3a800000, v166
	v_mul_f32_e32 v137, 0x4f800000, v136
	v_cmp_gt_f32_e32 vcc, s84, v136
	s_nop 1
	v_cndmask_b32_e32 v136, v136, v137, vcc
	v_sqrt_f32_e32 v137, v136
	s_nop 0
	v_add_u32_e32 v168, -1, v137
	v_add_u32_e32 v169, 1, v137
	v_fma_f32 v170, -v168, v137, v136
	v_fma_f32 v171, -v169, v137, v136
	v_cmp_ge_f32_e64 s[0:1], 0, v170
	s_nop 1
	v_cndmask_b32_e64 v137, v137, v168, s[0:1]
	v_cmp_lt_f32_e64 s[0:1], 0, v171
	s_nop 1
	v_cndmask_b32_e64 v137, v137, v169, s[0:1]
	v_mul_f32_e32 v168, 0x37800000, v137
	v_cndmask_b32_e32 v137, v137, v168, vcc
	v_cmp_class_f32_e32 vcc, v136, v167
	s_nop 1
	v_cndmask_b32_e32 v136, v137, v136, vcc
	v_div_scale_f32 v137, s[0:1], v136, v136, 1.0
	v_rcp_f32_e32 v168, v137
	v_div_scale_f32 v169, vcc, 1.0, v136, 1.0
	s_mov_b64 s[0:1], 0
	v_fma_f32 v170, -v137, v168, 1.0
	v_fmac_f32_e32 v168, v170, v168
	v_mul_f32_e32 v170, v169, v168
	v_fma_f32 v171, -v137, v170, v169
	v_fmac_f32_e32 v170, v171, v168
	v_fma_f32 v137, -v137, v170, v169
	v_div_fmas_f32 v137, v137, v168, v170
	v_div_fixup_f32 v168, v137, v136, 1.0

; __device__ __forceinline__ unsigned cvt_pk_bf16(float lo, float hi) { unsigned r; asm volatile("v_cvt_pk_bf16_f32 %0, %1, %2" : "=v"(r) : "v"(lo), "v"(hi)); return r; }
; #define PG8_BAR __builtin_amdgcn_s_barrier()
;     __device__ __forceinline__ void operator()(const f32x4 (&acc)[2][2][4][2], const Unit& u, int wr, int wc, int fr, int fq) const {
;         const int row0 = u.pm * BM + wr * 64 + fr, col0 = u.pn * HALF + wc * 32 + 8 * fq; const bool tab = (u.pm == rt_pm);
; #pragma unroll
;         for (int ai = 0; ai < 2; ++ai)
; #pragma unroll
;             for (int m = 0; m < 4; ++m) {
;                 const int row = row0 + ai * HALF + m * 16; const float r = tab ? rtab[row - u.pm * BM] : row_rstd(ss, row);
;                 const float c = r * -1.4426950408889634f, r2 = r * r;
;                 const f32x4 G0 = acc[ai][0][m][0], G1 = acc[ai][0][m][1], U0 = acc[ai][1][m][0], U1 = acc[ai][1][m][1];
;                 const f32x2 h0 = swiglu_pk((f32x2){G0[0], G0[1]}, (f32x2){U0[0], U0[1]}, c, r2), h1 = swiglu_pk((f32x2){G0[2], G0[3]}, (f32x2){U0[2], U0[3]}, c, r2);
;                 const f32x2 h2 = swiglu_pk((f32x2){G1[0], G1[1]}, (f32x2){U1[0], U1[1]}, c, r2), h3 = swiglu_pk((f32x2){G1[2], G1[3]}, (f32x2){U1[2], U1[3]}, c, r2);
;                 u32x4 w;
;                 w.x = cvt_pk_bf16(h0.x, h0.y); w.y = cvt_pk_bf16(h1.x, h1.y); w.z = cvt_pk_bf16(h2.x, h2.y); w.w = cvt_pk_bf16(h3.x, h3.y);
;                 *(u32x4*)(H + (size_t)row * ldh + col0) = w;
; template <class Epi, class Sched, bool ALIGN_EPI = false, bool SP2 = false>
; __device__ __forceinline__ void gemm_phase(PG8_LAS unsigned char* lds, const Gemm g, const Sched& S, const Epi& E) {
;     ...
;         if constexpr (ALIGN_EPI) { if (wr == 0) PG8_BAR; }
.LBB0_141:
	s_waitcnt lgkmcnt(0)
	v_mul_f32_e32 v170, 0xbfb8aa3b, v168
	v_pk_mul_f32 v[136:137], v[124:125], v[170:171] op_sel_hi:[1,0]
	v_pk_mul_f32 v[178:179], v[126:127], v[170:171] op_sel_hi:[1,0]
	v_exp_f32_e32 v176, v136
	v_exp_f32_e32 v177, v137
	v_exp_f32_e32 v178, v178
	v_exp_f32_e32 v179, v179
	v_pk_mul_f32 v[122:123], v[126:127], v[122:123]
	v_pk_add_f32 v[176:177], v[176:177], 1.0 op_sel_hi:[1,0]
	v_mul_f32_e32 v168, v168, v168
	v_rcp_f32_e32 v176, v176
	v_rcp_f32_e32 v177, v177
	v_pk_add_f32 v[126:127], v[178:179], 1.0 op_sel_hi:[1,0]
	v_pk_mul_f32 v[120:121], v[124:125], v[120:121]
	v_rcp_f32_e32 v126, v126
	v_rcp_f32_e32 v127, v127
	v_pk_mul_f32 v[124:125], v[168:169], v[176:177] op_sel_hi:[0,1]
	v_pk_mul_f32 v[176:177], v[116:117], v[170:171] op_sel_hi:[1,0]
	v_pk_mul_f32 v[120:121], v[120:121], v[124:125]
	v_exp_f32_e32 v176, v176
	v_exp_f32_e32 v177, v177
	v_pk_mul_f32 v[124:125], v[168:169], v[126:127] op_sel_hi:[0,1]
	v_pk_mul_f32 v[126:127], v[118:119], v[170:171] op_sel_hi:[1,0]
	v_pk_mul_f32 v[122:123], v[122:123], v[124:125]
	v_exp_f32_e32 v126, v126
	v_exp_f32_e32 v127, v127
	v_pk_add_f32 v[124:125], v[176:177], 1.0 op_sel_hi:[1,0]
	v_pk_mul_f32 v[114:115], v[118:119], v[114:115]
	v_rcp_f32_e32 v124, v124
	v_rcp_f32_e32 v125, v125
	v_pk_add_f32 v[118:119], v[126:127], 1.0 op_sel_hi:[1,0]
	v_pk_mul_f32 v[112:113], v[116:117], v[112:113]
	v_rcp_f32_e32 v118, v118
	v_rcp_f32_e32 v119, v119
	v_pk_mul_f32 v[116:117], v[168:169], v[124:125] op_sel_hi:[0,1]
	v_pk_mul_f32 v[116:117], v[112:113], v[116:117]
	v_lshl_or_b32 v136, s6, 7, v150
	v_pk_mul_f32 v[112:113], v[168:169], v[118:119] op_sel_hi:[0,1]
	v_pk_mul_f32 v[118:119], v[114:115], v[112:113]
	v_cvt_pk_bf16_f32 v112, v120, v121
	v_cvt_pk_bf16_f32 v113, v122, v123
	v_cvt_pk_bf16_f32 v114, v116, v117
	v_mov_b64_e32 v[116:117], s[78:79]
	v_mad_u64_u32 v[116:117], s[0:1], v138, s85, v[116:117]
	v_cvt_pk_bf16_f32 v115, v118, v119
	v_mov_b32_e32 v118, v117
	v_mad_u64_u32 v[118:119], s[0:1], v139, s85, v[118:119]
	v_ashrrev_i32_e32 v137, 31, v136
	v_mov_b32_e32 v117, v118
	v_lshl_add_u64 v[116:117], v[136:137], 1, v[116:117]
	global_store_dwordx4 v[116:117], v[112:115], off
	s_cmp_eq_u64 s[12:13], 0
	s_cbranch_scc1 .Lalign_p1
	s_barrier
.Lalign_p1:
	s_mov_b64 s[6:7], -1
	s_andn2_b64 vcc, exec, s[34:35]
	v_or_b32_e32 v112, 16, v138
	v_cndmask_b32_e64 v113, 0, 1, s[34:35]
	v_cmp_ne_u32_e64 s[0:1], 1, v113
	v_ashrrev_i32_e32 v113, 31, v112
	s_cbranch_vccnz .LBB0_143
	v_lshlrev_b64 v[114:115], 6, v[112:113]
	v_lshl_add_u64 v[126:127], s[72:73], 0, v[114:115]
	global_load_dwordx4 v[114:117], v[126:127], off
	global_load_dwordx4 v[118:121], v[126:127], off offset:32
	global_load_dwordx4 v[122:125], v[126:127], off offset:16
	global_load_dwordx4 v[168:171], v[126:127], off offset:48
	s_waitcnt vmcnt(0)
	v_mov_b32_e32 v126, v114
	v_mov_b32_e32 v127, v118
	v_mov_b32_e32 v118, v115
	v_mov_b32_e32 v114, v116
	v_mov_b32_e32 v115, v120
	v_mov_b32_e32 v120, v117
	v_mov_b32_e32 v116, v122
	v_mov_b32_e32 v117, v168
	v_mov_b32_e32 v168, v123
	v_mov_b32_e32 v122, v124
	v_mov_b32_e32 v123, v170
	v_mov_b32_e32 v170, v125
	v_pk_add_f32 v[118:119], v[126:127], v[118:119]
	v_pk_add_f32 v[114:115], v[114:115], v[120:121]
	v_pk_add_f32 v[116:117], v[116:117], v[168:169]
	v_pk_add_f32 v[120:121], v[122:123], v[170:171]
	v_pk_add_f32 v[114:115], v[118:119], v[114:115]
	v_pk_add_f32 v[116:117], v[116:117], v[120:121]
	s_nop 0
	v_pk_add_f32 v[114:115], v[114:115], v[116:117]
	s_nop 0
	v_add_f32_e32 v114, v114, v115
	v_fmamk_f32 v114, v114, 0x3a800000, v166
	v_mul_f32_e32 v115, 0x4f800000, v114
	v_cmp_gt_f32_e32 vcc, s84, v114
	s_nop 1
	v_cndmask_b32_e32 v114, v114, v115, vcc
	v_sqrt_f32_e32 v115, v114
	s_nop 0
	v_add_u32_e32 v116, -1, v115
	v_add_u32_e32 v117, 1, v115
	v_fma_f32 v118, -v116, v115, v114
	v_fma_f32 v119, -v117, v115, v114
	v_cmp_ge_f32_e64 s[6:7], 0, v118
	s_nop 1
	v_cndmask_b32_e64 v115, v115, v116, s[6:7]
	v_cmp_lt_f32_e64 s[6:7], 0, v119
	s_nop 1
	v_cndmask_b32_e64 v115, v115, v117, s[6:7]
	v_mul_f32_e32 v116, 0x37800000, v115
	v_cndmask_b32_e32 v115, v115, v116, vcc
	v_cmp_class_f32_e32 vcc, v114, v167
	s_nop 1
	v_cndmask_b32_e32 v114, v115, v114, vcc
	v_div_scale_f32 v115, s[6:7], v114, v114, 1.0
	v_rcp_f32_e32 v116, v115
	v_div_scale_f32 v117, vcc, 1.0, v114, 1.0
	s_mov_b64 s[6:7], 0
	v_fma_f32 v118, -v115, v116, 1.0
	v_fmac_f32_e32 v116, v118, v116
	v_mul_f32_e32 v118, v117, v116
	v_fma_f32 v119, -v115, v118, v117
	v_fmac_f32_e32 v118, v119, v116
	v_fma_f32 v115, -v115, v118, v117
	v_div_fmas_f32 v115, v115, v116, v118
	v_div_fixup_f32 v114, v115, v114, 1.0

; #define PG8_STAGE(bufoff, gbase, voff) do { _Pragma("unroll") for (int _i = 0; _i < 2; ++_i) \
;         __builtin_amdgcn_global_load_lds((const unsigned*)((const char*)(gbase) + (voff)[_i]), (PG8_LAS unsigned*)(lds + (bufoff) + ldsw + _i * 8192), 16, 0, 0); } while (0)
; #define PG8_LDA(dst, b, h) do { _Pragma("unroll") for (int m = 0; m < 4; ++m) _Pragma("unroll") for (int k = 0; k < 2; ++k) dst[m][k] = *(const PG8_LAS bf16x8*)(lds + PG8_SA(b, h) + aoff + m * 2048 + k * 1024); } while (0)
; #define PG8_LDB(dst, b, h) do { _Pragma("unroll") for (int n = 0; n < 2; ++n) _Pragma("unroll") for (int k = 0; k < 2; ++k) dst[n][k] = *(const PG8_LAS bf16x8*)(lds + PG8_SB(b, h) + boff + n * 2048 + k * 1024); } while (0)
; #define PG8_MMA(ai, bj, At, Bt) do { __builtin_amdgcn_s_setprio(1); _Pragma("unroll") for (int m = 0; m < 4; ++m) _Pragma("unroll") for (int n = 0; n < 2; ++n) _Pragma("unroll") for (int k = 0; k < 2; ++k) \
;         acc[ai][bj][m][n] = __builtin_amdgcn_mfma_f32_16x16x32_bf16(Bt[n][k], At[m][k], acc[ai][bj][m][n], 0, 0, 0); __builtin_amdgcn_s_setprio(0); } while (0)
; #define PG8_WAIT_V(n) asm volatile("s_waitcnt vmcnt(" #n ")" ::: "memory")
; #define PG8_WAIT_L(n) asm volatile("s_waitcnt lgkmcnt(" #n ")" ::: "memory")
; #define PG8_BAR __builtin_amdgcn_s_barrier()
; #define PG8_SCHED __builtin_amdgcn_sched_barrier(0)
; template <class Epi, class Sched, bool ALIGN_EPI = false, bool SP2 = false>
; __device__ __forceinline__ void gemm_phase(PG8_LAS unsigned char* lds, const Gemm g, const Sched& S, const Epi& E) {
;     ...
;             PG8_LDB(B0, 0, 0); PG8_LDB(B1, 0, 1); PG8_SCHED; PG8_LDA(At, 0, 0); PG8_STAGE(PG8_SA(1, 1), a1 + hstep, voffA);
;             PG8_WAIT_V(8); PG8_WAIT_L(0); PG8_BAR; PG8_MMA(0, 0, At, B0); PG8_MMA(0, 1, At, B1); PG8_BAR; PG8_SCHED;
;             PG8_LDA(At, 0, 1); PG8_STAGE(PG8_SB(0, 0), b2, voffB); PG8_STAGE(PG8_SB(0, 1), b2 + hstep, voffB); PG8_STAGE(PG8_SA(0, 0), a2, voffA);
;             PG8_WAIT_V(8); PG8_WAIT_L(0); PG8_BAR; PG8_MMA(1, 0, At, B0); PG8_MMA(1, 1, At, B1); PG8_BAR; PG8_SCHED;
.LBB0_1322:
	ds_read_b128 v[136:139], v144
	ds_read_b128 v[174:177], v144 offset:1024
	ds_read_b128 v[178:181], v144 offset:2048
	ds_read_b128 v[182:185], v144 offset:3072
	ds_read_b128 v[186:189], v145
	ds_read_b128 v[190:193], v145 offset:1024
	ds_read_b128 v[194:197], v145 offset:2048
	ds_read_b128 v[198:201], v145 offset:3072
	s_add_u32 s26, s24, 0xfffc0080
	s_addc_u32 s27, s25, -1
	s_cmp_eq_u32 s50, 12
	s_cselect_b32 s29, s1, s27
	s_cselect_b32 s28, s11, s26
	s_cselect_b32 s27, s17, s49
	s_cselect_b32 s26, s19, s48
	v_lshl_add_u64 v[150:151], s[24:25], 0, v[128:129]
	s_add_i32 m0, s33, 0xc000
	ds_read_b128 v[202:205], v146
	ds_read_b128 v[206:209], v146 offset:1024
	ds_read_b128 v[210:213], v146 offset:2048
	ds_read_b128 v[214:217], v146 offset:3072
	ds_read_b128 v[218:221], v146 offset:4096
	ds_read_b128 v[222:225], v146 offset:5120
	ds_read_b128 v[226:229], v146 offset:6144
	ds_read_b128 v[236:239], v146 offset:7168
	global_load_lds_dwordx4 v[150:151], off
	v_lshl_add_u64 v[150:151], s[24:25], 0, v[130:131]
	s_add_i32 m0, s33, 0xe000
	s_nop 0
	global_load_lds_dwordx4 v[150:151], off
	s_waitcnt vmcnt(8)
	s_waitcnt lgkmcnt(0)
	s_setprio 1
	s_barrier
	v_mfma_f32_16x16x32_bf16 v[124:127], v[136:139], v[202:205], v[124:127]
	v_mfma_f32_16x16x32_bf16 v[116:119], v[178:181], v[202:205], v[116:119]
	v_mfma_f32_16x16x32_bf16 v[108:111], v[136:139], v[210:213], v[108:111]
	v_mfma_f32_16x16x32_bf16 v[100:103], v[178:181], v[210:213], v[100:103]
	v_mfma_f32_16x16x32_bf16 v[92:95], v[136:139], v[218:221], v[92:95]
	v_mfma_f32_16x16x32_bf16 v[84:87], v[178:181], v[218:221], v[84:87]
	v_mfma_f32_16x16x32_bf16 v[76:79], v[136:139], v[226:229], v[76:79]
	v_mfma_f32_16x16x32_bf16 v[68:71], v[178:181], v[226:229], v[68:71]
	v_mfma_f32_16x16x32_bf16 v[124:127], v[174:177], v[206:209], v[124:127]
	v_mfma_f32_16x16x32_bf16 v[116:119], v[182:185], v[206:209], v[116:119]
	v_mfma_f32_16x16x32_bf16 v[108:111], v[174:177], v[214:217], v[108:111]
	v_mfma_f32_16x16x32_bf16 v[100:103], v[182:185], v[214:217], v[100:103]
	v_mfma_f32_16x16x32_bf16 v[92:95], v[174:177], v[222:225], v[92:95]
	v_mfma_f32_16x16x32_bf16 v[84:87], v[182:185], v[222:225], v[84:87]
	v_mfma_f32_16x16x32_bf16 v[76:79], v[174:177], v[236:239], v[76:79]
	v_mfma_f32_16x16x32_bf16 v[68:71], v[182:185], v[236:239], v[68:71]
	s_setprio 0
	s_setprio 1
	v_mfma_f32_16x16x32_bf16 v[120:123], v[186:189], v[202:205], v[120:123]
	v_mfma_f32_16x16x32_bf16 v[112:115], v[194:197], v[202:205], v[112:115]
	v_mfma_f32_16x16x32_bf16 v[104:107], v[186:189], v[210:213], v[104:107]
	v_mfma_f32_16x16x32_bf16 v[96:99], v[194:197], v[210:213], v[96:99]
	v_mfma_f32_16x16x32_bf16 v[88:91], v[186:189], v[218:221], v[88:91]
	v_mfma_f32_16x16x32_bf16 v[80:83], v[194:197], v[218:221], v[80:83]
	v_mfma_f32_16x16x32_bf16 v[72:75], v[186:189], v[226:229], v[72:75]
	v_mfma_f32_16x16x32_bf16 v[64:67], v[194:197], v[226:229], v[64:67]
	v_mfma_f32_16x16x32_bf16 v[120:123], v[190:193], v[206:209], v[120:123]
	v_mfma_f32_16x16x32_bf16 v[112:115], v[198:201], v[206:209], v[112:115]
	v_mfma_f32_16x16x32_bf16 v[104:107], v[190:193], v[214:217], v[104:107]
	v_mfma_f32_16x16x32_bf16 v[96:99], v[198:201], v[214:217], v[96:99]
	v_mfma_f32_16x16x32_bf16 v[88:91], v[190:193], v[222:225], v[88:91]
	v_mfma_f32_16x16x32_bf16 v[80:83], v[198:201], v[222:225], v[80:83]
	v_mfma_f32_16x16x32_bf16 v[72:75], v[190:193], v[236:239], v[72:75]
	v_mfma_f32_16x16x32_bf16 v[64:67], v[198:201], v[236:239], v[64:67]
	s_barrier
	s_setprio 0
	s_add_i32 s51, s44, s3
	v_lshl_add_u64 v[150:151], s[26:27], 0, v[158:159]
	s_mov_b32 m0, s51
	ds_read_b128 v[202:205], v146 offset:16384
	ds_read_b128 v[206:209], v146 offset:17408
	ds_read_b128 v[210:213], v146 offset:18432
	ds_read_b128 v[214:217], v146 offset:19456
	ds_read_b128 v[218:221], v146 offset:20480
	ds_read_b128 v[222:225], v146 offset:21504
	ds_read_b128 v[226:229], v146 offset:22528
	ds_read_b128 v[236:239], v146 offset:23552
	global_load_lds_dwordx4 v[150:151], off
	s_add_i32 m0, s51, 0x2000
	s_add_u32 s52, s26, 0x40000
	v_lshl_add_u64 v[246:247], s[26:27], 0, v[162:163]
	s_addc_u32 s53, s27, 0
	s_add_i32 s51, s45, s3
	global_load_lds_dwordx4 v[246:247], off
	v_lshl_add_u64 v[248:249], s[52:53], 0, v[158:159]
	s_mov_b32 m0, s51
	v_lshl_add_u64 v[250:251], s[28:29], 0, v[160:161]
	global_load_lds_dwordx4 v[248:249], off
	v_lshl_add_u64 v[248:249], s[52:53], 0, v[162:163]
	s_add_i32 m0, s51, 0x2000
	s_nop 0
	global_load_lds_dwordx4 v[248:249], off
	v_lshl_add_u64 v[248:249], s[28:29], 0, v[156:157]
	s_mov_b32 m0, s33
	s_nop 0
	global_load_lds_dwordx4 v[248:249], off
	s_mov_b32 m0, s34
	s_nop 0
	global_load_lds_dwordx4 v[250:251], off
	s_waitcnt vmcnt(8)
	s_waitcnt lgkmcnt(0)
	s_setprio 1
	s_barrier
; #define PG8_STAGE(bufoff, gbase, voff) do { _Pragma("unroll") for (int _i = 0; _i < 2; ++_i) \
;         __builtin_amdgcn_global_load_lds((const unsigned*)((const char*)(gbase) + (voff)[_i]), (PG8_LAS unsigned*)(lds + (bufoff) + ldsw + _i * 8192), 16, 0, 0); } while (0)
; #define PG8_LDA(dst, b, h) do { _Pragma("unroll") for (int m = 0; m < 4; ++m) _Pragma("unroll") for (int k = 0; k < 2; ++k) dst[m][k] = *(const PG8_LAS bf16x8*)(lds + PG8_SA(b, h) + aoff + m * 2048 + k * 1024); } while (0)
; #define PG8_LDB(dst, b, h) do { _Pragma("unroll") for (int n = 0; n < 2; ++n) _Pragma("unroll") for (int k = 0; k < 2; ++k) dst[n][k] = *(const PG8_LAS bf16x8*)(lds + PG8_SB(b, h) + boff + n * 2048 + k * 1024); } while (0)
; #define PG8_MMA(ai, bj, At, Bt) do { __builtin_amdgcn_s_setprio(1); _Pragma("unroll") for (int m = 0; m < 4; ++m) _Pragma("unroll") for (int n = 0; n < 2; ++n) _Pragma("unroll") for (int k = 0; k < 2; ++k) \
;         acc[ai][bj][m][n] = __builtin_amdgcn_mfma_f32_16x16x32_bf16(Bt[n][k], At[m][k], acc[ai][bj][m][n], 0, 0, 0); __builtin_amdgcn_s_setprio(0); } while (0)
; #define PG8_WAIT_V(n) asm volatile("s_waitcnt vmcnt(" #n ")" ::: "memory")
; #define PG8_WAIT_L(n) asm volatile("s_waitcnt lgkmcnt(" #n ")" ::: "memory")
; #define PG8_BAR __builtin_amdgcn_s_barrier()
; #define PG8_SCHED __builtin_amdgcn_sched_barrier(0)
; template <class Epi, class Sched, bool ALIGN_EPI = false, bool SP2 = false>
; __device__ __forceinline__ void gemm_phase(PG8_LAS unsigned char* lds, const Gemm g, const Sched& S, const Epi& E) {
;     ...
;             PG8_WAIT_V(8); PG8_WAIT_L(0); PG8_BAR; PG8_MMA(1, 0, At, B0); PG8_MMA(1, 1, At, B1); PG8_BAR; PG8_SCHED;
;             PG8_LDB(B0, 1, 0); PG8_LDB(B1, 1, 1); PG8_SCHED; PG8_LDA(At, 1, 0); PG8_STAGE(PG8_SA(0, 1), a2 + hstep, voffA);
;             PG8_WAIT_V(8); PG8_WAIT_L(0); PG8_BAR; PG8_MMA(0, 0, At, B0); PG8_MMA(0, 1, At, B1); PG8_BAR; PG8_SCHED;
	v_mfma_f32_16x16x32_bf16 v[60:63], v[136:139], v[202:205], v[60:63]
	v_mfma_f32_16x16x32_bf16 v[52:55], v[178:181], v[202:205], v[52:55]
	v_mfma_f32_16x16x32_bf16 v[44:47], v[136:139], v[210:213], v[44:47]
	v_mfma_f32_16x16x32_bf16 v[36:39], v[178:181], v[210:213], v[36:39]
	v_mfma_f32_16x16x32_bf16 v[28:31], v[136:139], v[218:221], v[28:31]
	v_mfma_f32_16x16x32_bf16 v[20:23], v[178:181], v[218:221], v[20:23]
	v_mfma_f32_16x16x32_bf16 v[12:15], v[136:139], v[226:229], v[12:15]
	v_mfma_f32_16x16x32_bf16 v[4:7], v[178:181], v[226:229], v[4:7]
	v_mfma_f32_16x16x32_bf16 v[60:63], v[174:177], v[206:209], v[60:63]
	v_mfma_f32_16x16x32_bf16 v[52:55], v[182:185], v[206:209], v[52:55]
	v_mfma_f32_16x16x32_bf16 v[44:47], v[174:177], v[214:217], v[44:47]
	v_mfma_f32_16x16x32_bf16 v[36:39], v[182:185], v[214:217], v[36:39]
	v_mfma_f32_16x16x32_bf16 v[28:31], v[174:177], v[222:225], v[28:31]
	v_mfma_f32_16x16x32_bf16 v[20:23], v[182:185], v[222:225], v[20:23]
	v_mfma_f32_16x16x32_bf16 v[12:15], v[174:177], v[236:239], v[12:15]
	v_mfma_f32_16x16x32_bf16 v[4:7], v[182:185], v[236:239], v[4:7]
	s_setprio 0
	s_setprio 1
	v_mfma_f32_16x16x32_bf16 v[56:59], v[186:189], v[202:205], v[56:59]
	v_mfma_f32_16x16x32_bf16 v[48:51], v[194:197], v[202:205], v[48:51]
	v_mfma_f32_16x16x32_bf16 v[40:43], v[186:189], v[210:213], v[40:43]
	v_mfma_f32_16x16x32_bf16 v[32:35], v[194:197], v[210:213], v[32:35]
	v_mfma_f32_16x16x32_bf16 v[24:27], v[186:189], v[218:221], v[24:27]
	v_mfma_f32_16x16x32_bf16 v[16:19], v[194:197], v[218:221], v[16:19]
	v_mfma_f32_16x16x32_bf16 v[8:11], v[186:189], v[226:229], v[8:11]
	v_mfma_f32_16x16x32_bf16 v[0:3], v[194:197], v[226:229], v[0:3]
	v_mfma_f32_16x16x32_bf16 v[56:59], v[190:193], v[206:209], v[56:59]
	v_mfma_f32_16x16x32_bf16 v[48:51], v[198:201], v[206:209], v[48:51]
	v_mfma_f32_16x16x32_bf16 v[40:43], v[190:193], v[214:217], v[40:43]
	v_mfma_f32_16x16x32_bf16 v[32:35], v[198:201], v[214:217], v[32:35]
	v_mfma_f32_16x16x32_bf16 v[24:27], v[190:193], v[222:225], v[24:27]
	v_mfma_f32_16x16x32_bf16 v[16:19], v[198:201], v[222:225], v[16:19]
	v_mfma_f32_16x16x32_bf16 v[8:11], v[190:193], v[236:239], v[8:11]
	v_mfma_f32_16x16x32_bf16 v[0:3], v[198:201], v[236:239], v[0:3]
	s_barrier
	s_setprio 0
	s_add_i32 s51, 0, 0x18000
	v_add_u32_e32 v149, s51, v141
	s_add_i32 s52, 0, 0x1c000
	ds_read_b128 v[136:139], v149
	ds_read_b128 v[174:177], v149 offset:1024
	ds_read_b128 v[178:181], v149 offset:2048
	ds_read_b128 v[182:185], v149 offset:3072
	v_add_u32_e32 v149, s52, v141
	ds_read_b128 v[186:189], v149
	ds_read_b128 v[190:193], v149 offset:1024
	ds_read_b128 v[194:197], v149 offset:2048
	ds_read_b128 v[198:201], v149 offset:3072
	s_add_u32 s28, s28, 0x40000
	s_addc_u32 s29, s29, 0
	s_mov_b32 m0, s35
	v_lshl_add_u64 v[252:253], s[28:29], 0, v[156:157]
	ds_read_b128 v[202:205], v146 offset:32768
	ds_read_b128 v[206:209], v146 offset:33792
	ds_read_b128 v[210:213], v146 offset:34816
	ds_read_b128 v[214:217], v146 offset:35840
	ds_read_b128 v[218:221], v146 offset:36864
	ds_read_b128 v[222:225], v146 offset:37888
	ds_read_b128 v[226:229], v146 offset:38912
	ds_read_b128 v[236:239], v146 offset:39936
	global_load_lds_dwordx4 v[252:253], off
	v_lshl_add_u64 v[252:253], s[28:29], 0, v[160:161]
	s_mov_b32 m0, s36
	s_nop 0
	global_load_lds_dwordx4 v[252:253], off
	s_waitcnt vmcnt(8)
	s_waitcnt lgkmcnt(0)
	s_setprio 1
	s_barrier
	v_mfma_f32_16x16x32_bf16 v[124:127], v[136:139], v[202:205], v[124:127]
	v_mfma_f32_16x16x32_bf16 v[116:119], v[178:181], v[202:205], v[116:119]
	v_mfma_f32_16x16x32_bf16 v[108:111], v[136:139], v[210:213], v[108:111]
	v_mfma_f32_16x16x32_bf16 v[100:103], v[178:181], v[210:213], v[100:103]
	v_mfma_f32_16x16x32_bf16 v[92:95], v[136:139], v[218:221], v[92:95]
	v_mfma_f32_16x16x32_bf16 v[84:87], v[178:181], v[218:221], v[84:87]
	v_mfma_f32_16x16x32_bf16 v[76:79], v[136:139], v[226:229], v[76:79]
	v_mfma_f32_16x16x32_bf16 v[68:71], v[178:181], v[226:229], v[68:71]
	v_mfma_f32_16x16x32_bf16 v[124:127], v[174:177], v[206:209], v[124:127]
	v_mfma_f32_16x16x32_bf16 v[116:119], v[182:185], v[206:209], v[116:119]
	v_mfma_f32_16x16x32_bf16 v[108:111], v[174:177], v[214:217], v[108:111]
	v_mfma_f32_16x16x32_bf16 v[100:103], v[182:185], v[214:217], v[100:103]
	v_mfma_f32_16x16x32_bf16 v[92:95], v[174:177], v[222:225], v[92:95]
	v_mfma_f32_16x16x32_bf16 v[84:87], v[182:185], v[222:225], v[84:87]
	v_mfma_f32_16x16x32_bf16 v[76:79], v[174:177], v[236:239], v[76:79]
	v_mfma_f32_16x16x32_bf16 v[68:71], v[182:185], v[236:239], v[68:71]
	s_setprio 0
	s_setprio 1
	v_mfma_f32_16x16x32_bf16 v[120:123], v[186:189], v[202:205], v[120:123]
	v_mfma_f32_16x16x32_bf16 v[112:115], v[194:197], v[202:205], v[112:115]
	v_mfma_f32_16x16x32_bf16 v[104:107], v[186:189], v[210:213], v[104:107]
	v_mfma_f32_16x16x32_bf16 v[96:99], v[194:197], v[210:213], v[96:99]
	v_mfma_f32_16x16x32_bf16 v[88:91], v[186:189], v[218:221], v[88:91]
	v_mfma_f32_16x16x32_bf16 v[80:83], v[194:197], v[218:221], v[80:83]
	v_mfma_f32_16x16x32_bf16 v[72:75], v[186:189], v[226:229], v[72:75]
	v_mfma_f32_16x16x32_bf16 v[64:67], v[194:197], v[226:229], v[64:67]
	v_mfma_f32_16x16x32_bf16 v[120:123], v[190:193], v[206:209], v[120:123]
	v_mfma_f32_16x16x32_bf16 v[112:115], v[198:201], v[206:209], v[112:115]
	v_mfma_f32_16x16x32_bf16 v[104:107], v[190:193], v[214:217], v[104:107]
	v_mfma_f32_16x16x32_bf16 v[96:99], v[198:201], v[214:217], v[96:99]
	v_mfma_f32_16x16x32_bf16 v[88:91], v[190:193], v[222:225], v[88:91]
	v_mfma_f32_16x16x32_bf16 v[80:83], v[198:201], v[222:225], v[80:83]
	v_mfma_f32_16x16x32_bf16 v[72:75], v[190:193], v[236:239], v[72:75]
	v_mfma_f32_16x16x32_bf16 v[64:67], v[198:201], v[236:239], v[64:67]
	s_barrier
; __device__ __forceinline__ float row_rstd(const float* ss, int row) {
;     const f32x4* p = (const f32x4*)(ss + (size_t)row * 16);
;     const f32x4 a = p[0], b = p[1], c = p[2], d = p[3];
;     const float s = (((a[0] + a[1]) + (a[2] + a[3])) + ((b[0] + b[1]) + (b[2] + b[3]))) + (((c[0] + c[1]) + (c[2] + c[3])) + ((d[0] + d[1]) + (d[2] + d[3])));
; template <class Epi, class Sched, bool ALIGN_EPI = false, bool SP2 = false>
; __device__ __forceinline__ void gemm_phase(PG8_LAS unsigned char* lds, const Gemm g, const Sched& S, const Epi& E) {
;     ...
;             PG8_WAIT_V(8); PG8_WAIT_L(0); PG8_BAR; PG8_MMA(0, 0, At, B0); PG8_MMA(0, 1, At, B1); PG8_BAR; PG8_SCHED;
;             PG8_LDA(At, 1, 1); PG8_STAGE(PG8_SB(1, 0), b3, voffB); PG8_STAGE(PG8_SB(1, 1), b3 + hstep, voffB); PG8_STAGE(PG8_SA(1, 0), a3, voffA);
;             PG8_WAIT_V(8); PG8_WAIT_L(0); PG8_BAR; PG8_MMA(1, 0, At, B0); PG8_MMA(1, 1, At, B1); PG8_BAR; PG8_SCHED;
;             } else {
;             PG8_LDB(B0, 0, 0); PG8_SCHED; PG8_LDA(At, 0, 0); PG8_STAGE(PG8_SA(1, 1), a1 + hstep, voffA);
;             PG8_WAIT_L(8); PG8_BAR; PG8_WAIT_L(0); PG8_MMA(0, 0, At, B0); PG8_BAR; PG8_SCHED;
;             PG8_LDB(B1, 0, 1); PG8_STAGE(PG8_SB(0, 0), b2, voffB);
;             PG8_BAR; PG8_WAIT_L(0); PG8_MMA(0, 1, At, B1); PG8_BAR;
;             PG8_LDA(At, 0, 1); PG8_STAGE(PG8_SA(0, 0), a2, voffA);
;             PG8_BAR; PG8_WAIT_L(0); PG8_MMA(1, 0, At, B0); PG8_BAR; PG8_SCHED;
;             PG8_STAGE(PG8_SB(0, 1), b2 + hstep, voffB);
;             PG8_WAIT_V(6); PG8_BAR; PG8_MMA(1, 1, At, B1); PG8_BAR;
;             PG8_LDB(B0, 1, 0); PG8_SCHED; PG8_LDA(At, 1, 0); PG8_STAGE(PG8_SA(0, 1), a2 + hstep, voffA);
;             PG8_WAIT_L(8); PG8_BAR; PG8_WAIT_L(0); PG8_MMA(0, 0, At, B0); PG8_BAR; PG8_SCHED;
;             PG8_LDB(B1, 1, 1); PG8_STAGE(PG8_SB(1, 0), b3, voffB);
;             PG8_BAR; PG8_WAIT_L(0); PG8_MMA(0, 1, At, B1); PG8_BAR;
;             PG8_LDA(At, 1, 1); PG8_STAGE(PG8_SA(1, 0), a3, voffA);
;             PG8_BAR; PG8_WAIT_L(0); PG8_MMA(1, 0, At, B0); PG8_BAR; PG8_SCHED;
;             PG8_STAGE(PG8_SB(1, 1), b3 + hstep, voffB);
;             PG8_WAIT_V(6); PG8_BAR; PG8_MMA(1, 1, At, B1); PG8_BAR;
;             }
;         }
;         if constexpr (ALIGN_EPI) { if (wr == 0) PG8_BAR; }
;         if constexpr (!Epi::AFTER_DRAIN) { E(acc, cur, wr, wc, fr, fq); S.done(cur); }
	s_setprio 0
	s_add_i32 s28, s51, s3
	v_lshl_add_u64 v[150:151], v[150:151], 0, s[6:7]
	s_mov_b32 m0, s28
	ds_read_b128 v[202:205], v146 offset:49152
	ds_read_b128 v[206:209], v146 offset:50176
	ds_read_b128 v[210:213], v146 offset:51200
	ds_read_b128 v[214:217], v146 offset:52224
	ds_read_b128 v[218:221], v146 offset:53248
	ds_read_b128 v[222:225], v146 offset:54272
	ds_read_b128 v[226:229], v146 offset:55296
	ds_read_b128 v[236:239], v146 offset:56320
	global_load_lds_dwordx4 v[150:151], off
	s_add_i32 m0, s28, 0x2000
	s_add_u32 s26, s26, 0x40080
	v_lshl_add_u64 v[150:151], v[246:247], 0, s[6:7]
	s_addc_u32 s27, s27, 0
	s_add_i32 s28, s52, s3
	global_load_lds_dwordx4 v[150:151], off
	v_lshl_add_u64 v[150:151], s[26:27], 0, v[158:159]
	s_mov_b32 m0, s28
	s_nop 0
	global_load_lds_dwordx4 v[150:151], off
	v_lshl_add_u64 v[150:151], s[26:27], 0, v[162:163]
	s_add_i32 m0, s28, 0x2000
	s_nop 0
	global_load_lds_dwordx4 v[150:151], off
	v_lshl_add_u64 v[150:151], v[248:249], 0, s[6:7]
	s_mov_b32 m0, s38
	s_nop 0
	global_load_lds_dwordx4 v[150:151], off
	v_lshl_add_u64 v[150:151], v[250:251], 0, s[6:7]
	s_mov_b32 m0, s39
	s_nop 0
	global_load_lds_dwordx4 v[150:151], off
	s_waitcnt vmcnt(8)
	s_waitcnt lgkmcnt(0)
	s_setprio 1
	s_barrier
	v_mfma_f32_16x16x32_bf16 v[60:63], v[136:139], v[202:205], v[60:63]
	v_mfma_f32_16x16x32_bf16 v[52:55], v[178:181], v[202:205], v[52:55]
	v_mfma_f32_16x16x32_bf16 v[44:47], v[136:139], v[210:213], v[44:47]
	v_mfma_f32_16x16x32_bf16 v[36:39], v[178:181], v[210:213], v[36:39]
	v_mfma_f32_16x16x32_bf16 v[28:31], v[136:139], v[218:221], v[28:31]
	v_mfma_f32_16x16x32_bf16 v[20:23], v[178:181], v[218:221], v[20:23]
	v_mfma_f32_16x16x32_bf16 v[12:15], v[136:139], v[226:229], v[12:15]
	v_mfma_f32_16x16x32_bf16 v[4:7], v[178:181], v[226:229], v[4:7]
	v_mfma_f32_16x16x32_bf16 v[60:63], v[174:177], v[206:209], v[60:63]
	v_mfma_f32_16x16x32_bf16 v[52:55], v[182:185], v[206:209], v[52:55]
	v_mfma_f32_16x16x32_bf16 v[44:47], v[174:177], v[214:217], v[44:47]
	v_mfma_f32_16x16x32_bf16 v[36:39], v[182:185], v[214:217], v[36:39]
	v_mfma_f32_16x16x32_bf16 v[28:31], v[174:177], v[222:225], v[28:31]
	v_mfma_f32_16x16x32_bf16 v[20:23], v[182:185], v[222:225], v[20:23]
	v_mfma_f32_16x16x32_bf16 v[12:15], v[174:177], v[236:239], v[12:15]
	v_mfma_f32_16x16x32_bf16 v[4:7], v[182:185], v[236:239], v[4:7]
	s_setprio 0
	s_setprio 1
	v_mfma_f32_16x16x32_bf16 v[56:59], v[186:189], v[202:205], v[56:59]
	v_mfma_f32_16x16x32_bf16 v[48:51], v[194:197], v[202:205], v[48:51]
	v_mfma_f32_16x16x32_bf16 v[40:43], v[186:189], v[210:213], v[40:43]
	v_mfma_f32_16x16x32_bf16 v[32:35], v[194:197], v[210:213], v[32:35]
	v_mfma_f32_16x16x32_bf16 v[24:27], v[186:189], v[218:221], v[24:27]
	v_mfma_f32_16x16x32_bf16 v[16:19], v[194:197], v[218:221], v[16:19]
	v_mfma_f32_16x16x32_bf16 v[8:11], v[186:189], v[226:229], v[8:11]
	v_mfma_f32_16x16x32_bf16 v[0:3], v[194:197], v[226:229], v[0:3]
	v_mfma_f32_16x16x32_bf16 v[56:59], v[190:193], v[206:209], v[56:59]
	v_mfma_f32_16x16x32_bf16 v[48:51], v[198:201], v[206:209], v[48:51]
	v_mfma_f32_16x16x32_bf16 v[40:43], v[190:193], v[214:217], v[40:43]
	v_mfma_f32_16x16x32_bf16 v[32:35], v[198:201], v[214:217], v[32:35]
	v_mfma_f32_16x16x32_bf16 v[24:27], v[190:193], v[222:225], v[24:27]
	v_mfma_f32_16x16x32_bf16 v[16:19], v[198:201], v[222:225], v[16:19]
	v_mfma_f32_16x16x32_bf16 v[8:11], v[190:193], v[236:239], v[8:11]
	v_mfma_f32_16x16x32_bf16 v[0:3], v[198:201], v[236:239], v[0:3]
	s_barrier
	s_setprio 0
	s_add_i32 s50, s50, 2
	s_add_u32 s24, s24, 0x100
	s_addc_u32 s25, s25, 0
	s_add_u32 s48, s48, 0x100
	s_addc_u32 s49, s49, 0
	s_cmp_gt_u32 s50, 13
	s_cbranch_scc0 .LBB0_1322
.LBB0_1325:
	s_lshl_b32 s17, s0, 8
	s_cmp_lg_u32 s0, s2
	s_cselect_b64 s[24:25], -1, 0
	v_add_u32_e32 v138, s17, v140
	s_mov_b64 s[0:1], -1
	s_and_b64 vcc, exec, s[24:25]
	v_ashrrev_i32_e32 v139, 31, v138
	s_cbranch_vccz .LBB0_1327
	v_lshlrev_b64 v[136:137], 6, v[138:139]
	v_lshl_add_u64 v[136:137], s[12:13], 0, v[136:137]
	global_load_dwordx4 v[174:177], v[136:137], off
	global_load_dwordx4 v[178:181], v[136:137], off offset:32
	global_load_dwordx4 v[182:185], v[136:137], off offset:16
	global_load_dwordx4 v[186:189], v[136:137], off offset:48
	s_waitcnt vmcnt(0)
	v_mov_b32_e32 v136, v174
	v_mov_b32_e32 v137, v178
	v_mov_b32_e32 v178, v175
	v_mov_b32_e32 v150, v176
	v_mov_b32_e32 v151, v180
	v_mov_b32_e32 v180, v177
	v_mov_b32_e32 v174, v182
	v_mov_b32_e32 v175, v186
	v_mov_b32_e32 v186, v183
	v_mov_b32_e32 v176, v184
	v_mov_b32_e32 v177, v188
	v_mov_b32_e32 v188, v185
	v_pk_add_f32 v[136:137], v[136:137], v[178:179]
	v_pk_add_f32 v[150:151], v[150:151], v[180:181]
	v_pk_add_f32 v[174:175], v[174:175], v[186:187]
	v_pk_add_f32 v[176:177], v[176:177], v[188:189]
	v_pk_add_f32 v[136:137], v[136:137], v[150:151]
	v_pk_add_f32 v[150:151], v[174:175], v[176:177]
	s_nop 0
	v_pk_add_f32 v[136:137], v[136:137], v[150:151]
	s_nop 0
	v_add_f32_e32 v136, v136, v137
	v_fmamk_f32 v136, v136, 0x3a800000, v147
	v_mul_f32_e32 v137, 0x4f800000, v136
	v_cmp_gt_f32_e32 vcc, s46, v136
	s_nop 1
	v_cndmask_b32_e32 v136, v136, v137, vcc
	v_sqrt_f32_e32 v137, v136
	s_nop 0
	v_add_u32_e32 v149, -1, v137
	v_add_u32_e32 v150, 1, v137
	v_fma_f32 v151, -v149, v137, v136
	v_fma_f32 v165, -v150, v137, v136
	v_cmp_ge_f32_e64 s[0:1], 0, v151
	s_nop 1
	v_cndmask_b32_e64 v137, v137, v149, s[0:1]
	v_cmp_lt_f32_e64 s[0:1], 0, v165
	s_nop 1
	v_cndmask_b32_e64 v137, v137, v150, s[0:1]
	v_mul_f32_e32 v149, 0x37800000, v137
	v_cndmask_b32_e32 v137, v137, v149, vcc
	v_cmp_class_f32_e32 vcc, v136, v148
	s_nop 1
	v_cndmask_b32_e32 v136, v137, v136, vcc
	v_div_scale_f32 v137, s[0:1], v136, v136, 1.0
	v_rcp_f32_e32 v149, v137
	v_div_scale_f32 v150, vcc, 1.0, v136, 1.0
	s_mov_b64 s[0:1], 0
	v_fma_f32 v151, -v137, v149, 1.0
	v_fmac_f32_e32 v149, v151, v149
	v_mul_f32_e32 v151, v150, v149
	v_fma_f32 v165, -v137, v151, v150
	v_fmac_f32_e32 v151, v165, v149
	v_fma_f32 v137, -v137, v151, v150
	v_div_fmas_f32 v137, v137, v149, v151
	v_div_fixup_f32 v149, v137, v136, 1.0

; __device__ __forceinline__ unsigned cvt_pk_bf16(float lo, float hi) { unsigned r; asm volatile("v_cvt_pk_bf16_f32 %0, %1, %2" : "=v"(r) : "v"(lo), "v"(hi)); return r; }
; #define PG8_BAR __builtin_amdgcn_s_barrier()
;     __device__ __forceinline__ void operator()(const f32x4 (&acc)[2][2][4][2], const Unit& u, int wr, int wc, int fr, int fq) const {
;         const int row0 = u.pm * BM + wr * 64 + fr, col0 = u.pn * HALF + wc * 32 + 8 * fq; const bool tab = (u.pm == rt_pm);
; #pragma unroll
;         for (int ai = 0; ai < 2; ++ai)
; #pragma unroll
;             for (int m = 0; m < 4; ++m) {
;                 const int row = row0 + ai * HALF + m * 16; const float r = tab ? rtab[row - u.pm * BM] : row_rstd(ss, row);
;                 const float c = r * -1.4426950408889634f, r2 = r * r;
;                 const f32x4 G0 = acc[ai][0][m][0], G1 = acc[ai][0][m][1], U0 = acc[ai][1][m][0], U1 = acc[ai][1][m][1];
;                 const f32x2 h0 = swiglu_pk((f32x2){G0[0], G0[1]}, (f32x2){U0[0], U0[1]}, c, r2), h1 = swiglu_pk((f32x2){G0[2], G0[3]}, (f32x2){U0[2], U0[3]}, c, r2);
;                 const f32x2 h2 = swiglu_pk((f32x2){G1[0], G1[1]}, (f32x2){U1[0], U1[1]}, c, r2), h3 = swiglu_pk((f32x2){G1[2], G1[3]}, (f32x2){U1[2], U1[3]}, c, r2);
;                 u32x4 w;
;                 w.x = cvt_pk_bf16(h0.x, h0.y); w.y = cvt_pk_bf16(h1.x, h1.y); w.z = cvt_pk_bf16(h2.x, h2.y); w.w = cvt_pk_bf16(h3.x, h3.y);
;                 *(u32x4*)(H + (size_t)row * ldh + col0) = w;
; template <class Epi, class Sched, bool ALIGN_EPI = false, bool SP2 = false>
; __device__ __forceinline__ void gemm_phase(PG8_LAS unsigned char* lds, const Gemm g, const Sched& S, const Epi& E) {
;     ...
;         if constexpr (ALIGN_EPI) { if (wr == 0) PG8_BAR; }
.LBB0_1329:
	s_waitcnt lgkmcnt(0)
	v_mul_f32_e32 v150, 0xbfb8aa3b, v149
	v_pk_mul_f32 v[136:137], v[124:125], v[150:151] op_sel_hi:[1,0]
	v_pk_mul_f32 v[178:179], v[126:127], v[150:151] op_sel_hi:[1,0]
	v_exp_f32_e32 v174, v136
	v_exp_f32_e32 v175, v137
	v_exp_f32_e32 v178, v178
	v_exp_f32_e32 v179, v179
	v_pk_mul_f32 v[122:123], v[126:127], v[122:123]
	v_pk_add_f32 v[174:175], v[174:175], 1.0 op_sel_hi:[1,0]
	v_mul_f32_e32 v176, v149, v149
	v_rcp_f32_e32 v174, v174
	v_rcp_f32_e32 v175, v175
	v_pk_add_f32 v[126:127], v[178:179], 1.0 op_sel_hi:[1,0]
	v_pk_mul_f32 v[120:121], v[124:125], v[120:121]
	v_rcp_f32_e32 v126, v126
	v_rcp_f32_e32 v127, v127
	v_pk_mul_f32 v[124:125], v[176:177], v[174:175] op_sel_hi:[0,1]
	v_pk_mul_f32 v[174:175], v[116:117], v[150:151] op_sel_hi:[1,0]
	v_pk_mul_f32 v[120:121], v[120:121], v[124:125]
	v_exp_f32_e32 v174, v174
	v_exp_f32_e32 v175, v175
	v_pk_mul_f32 v[124:125], v[176:177], v[126:127] op_sel_hi:[0,1]
	v_pk_mul_f32 v[126:127], v[118:119], v[150:151] op_sel_hi:[1,0]
	v_pk_mul_f32 v[122:123], v[122:123], v[124:125]
	v_exp_f32_e32 v126, v126
	v_exp_f32_e32 v127, v127
	v_pk_add_f32 v[124:125], v[174:175], 1.0 op_sel_hi:[1,0]
	v_pk_mul_f32 v[114:115], v[118:119], v[114:115]
	v_rcp_f32_e32 v124, v124
	v_rcp_f32_e32 v125, v125
	v_pk_add_f32 v[118:119], v[126:127], 1.0 op_sel_hi:[1,0]
	v_pk_mul_f32 v[112:113], v[116:117], v[112:113]
	v_rcp_f32_e32 v118, v118
	v_rcp_f32_e32 v119, v119
	v_pk_mul_f32 v[116:117], v[176:177], v[124:125] op_sel_hi:[0,1]
	v_pk_mul_f32 v[116:117], v[112:113], v[116:117]
	v_lshl_or_b32 v136, s10, 7, v143
	v_pk_mul_f32 v[112:113], v[176:177], v[118:119] op_sel_hi:[0,1]
	v_pk_mul_f32 v[118:119], v[114:115], v[112:113]
	v_cvt_pk_bf16_f32 v112, v120, v121
	v_cvt_pk_bf16_f32 v113, v122, v123
	v_cvt_pk_bf16_f32 v114, v116, v117
	v_mov_b64_e32 v[116:117], s[78:79]
	v_mad_u64_u32 v[116:117], s[0:1], v138, s47, v[116:117]
	v_cvt_pk_bf16_f32 v115, v118, v119
	v_mov_b32_e32 v118, v117
	v_mad_u64_u32 v[118:119], s[0:1], v139, s47, v[118:119]
	v_ashrrev_i32_e32 v137, 31, v136
	v_mov_b32_e32 v117, v118
	v_lshl_add_u64 v[116:117], v[136:137], 1, v[116:117]
	global_store_dwordx4 v[116:117], v[112:115], off
	s_cmp_eq_u64 s[14:15], 0
	s_cbranch_scc1 .Lalign_p8
	s_barrier
.Lalign_p8:
	s_mov_b64 s[10:11], -1
	s_andn2_b64 vcc, exec, s[24:25]
	v_or_b32_e32 v112, 16, v138
	v_cndmask_b32_e64 v113, 0, 1, s[24:25]
	v_cmp_ne_u32_e64 s[0:1], 1, v113
	v_ashrrev_i32_e32 v113, 31, v112
	s_cbranch_vccnz .LBB0_1331
	v_lshlrev_b64 v[114:115], 6, v[112:113]
	v_lshl_add_u64 v[126:127], s[12:13], 0, v[114:115]
	global_load_dwordx4 v[114:117], v[126:127], off
	global_load_dwordx4 v[118:121], v[126:127], off offset:32
	global_load_dwordx4 v[122:125], v[126:127], off offset:16
	global_load_dwordx4 v[174:177], v[126:127], off offset:48
	s_waitcnt vmcnt(0)
	v_mov_b32_e32 v126, v114
	v_mov_b32_e32 v127, v118
	v_mov_b32_e32 v118, v115
	v_mov_b32_e32 v114, v116
	v_mov_b32_e32 v115, v120
	v_mov_b32_e32 v120, v117
	v_mov_b32_e32 v116, v122
	v_mov_b32_e32 v117, v174
	v_mov_b32_e32 v174, v123
	v_mov_b32_e32 v122, v124
	v_mov_b32_e32 v123, v176
	v_mov_b32_e32 v176, v125
	v_pk_add_f32 v[118:119], v[126:127], v[118:119]
	v_pk_add_f32 v[114:115], v[114:115], v[120:121]
	v_pk_add_f32 v[116:117], v[116:117], v[174:175]
	v_pk_add_f32 v[120:121], v[122:123], v[176:177]
	v_pk_add_f32 v[114:115], v[118:119], v[114:115]
	v_pk_add_f32 v[116:117], v[116:117], v[120:121]
	s_nop 0
	v_pk_add_f32 v[114:115], v[114:115], v[116:117]
	s_nop 0
	v_add_f32_e32 v114, v114, v115
	v_fmamk_f32 v114, v114, 0x3a800000, v147
	v_mul_f32_e32 v115, 0x4f800000, v114
	v_cmp_gt_f32_e32 vcc, s46, v114
	s_nop 1
	v_cndmask_b32_e32 v114, v114, v115, vcc
	v_sqrt_f32_e32 v115, v114
	s_nop 0
	v_add_u32_e32 v116, -1, v115
	v_add_u32_e32 v117, 1, v115
	v_fma_f32 v118, -v116, v115, v114
	v_fma_f32 v119, -v117, v115, v114
	v_cmp_ge_f32_e64 s[10:11], 0, v118
	s_nop 1
	v_cndmask_b32_e64 v115, v115, v116, s[10:11]
	v_cmp_lt_f32_e64 s[10:11], 0, v119
	s_nop 1
	v_cndmask_b32_e64 v115, v115, v117, s[10:11]
	v_mul_f32_e32 v116, 0x37800000, v115
	v_cndmask_b32_e32 v115, v115, v116, vcc
	v_cmp_class_f32_e32 vcc, v114, v148
	s_nop 1
	v_cndmask_b32_e32 v114, v115, v114, vcc
	v_div_scale_f32 v115, s[10:11], v114, v114, 1.0
	v_rcp_f32_e32 v116, v115
	v_div_scale_f32 v117, vcc, 1.0, v114, 1.0
	s_mov_b64 s[10:11], 0
	v_fma_f32 v118, -v115, v116, 1.0
	v_fmac_f32_e32 v116, v118, v116
	v_mul_f32_e32 v118, v117, v116
	v_fma_f32 v119, -v115, v118, v117
	v_fmac_f32_e32 v118, v119, v116
	v_fma_f32 v115, -v115, v118, v117
	v_div_fmas_f32 v115, v115, v116, v118
	v_div_fixup_f32 v114, v115, v114, 1.0
